# phase-1 row loop: all 8 gain/scale vector loads issued up front with counted waits (was 4 serialized load-store groups)
# speedup vs baseline: 1.0160x; 1.0015x over previous
; __device__ __forceinline__ unsigned pk2(float lo, float hi) { f32x2 v = {lo, hi}; bf16x2_t b = __builtin_convertvector(v, bf16x2_t); return __builtin_bit_cast(unsigned, b); }
; __global__ void __launch_bounds__(512, 2) fwd_kernel(Params P) {
;     ...
;         for (int row = gw; row < MR; row += NGW) {
;             const float* xr = row < NP ? xp + (size_t)row * DM : xs + (size_t)(row - NP) * DM;
;             const int b = row_batch(row); f32x4 v[4]; float ss = 0.f;
; #pragma unroll
;             for (int j = 0; j < 4; ++j) { v[j] = *(const f32x4*)(xr + 4 * lane + 256 * j); ss += v[j][0] * v[j][0] + v[j][1] * v[j][1] + v[j][2] * v[j][2] + v[j][3] * v[j][3]; }
;             ss = wave_sum(ss); if (lane == 0) SSQ[row] = ss;
; #pragma unroll
;             for (int j = 0; j < 4; ++j) { const int col = 4 * lane + 256 * j; const f32x4 gg = *(const f32x4*)(gsl + col); const f32x4 scl = *(const f32x4*)(mdl + (size_t)b * 9216 + col);
;                 const f32x4 hv = v[j] * gg * (scl + 1.0f); u32x2 o; o.x = pk2(hv[0], hv[1]); o.y = pk2(hv[2], hv[3]); *(u32x2*)(H + (size_t)row * DM + col) = o; }
.LBB0_171:
	s_or_b64 exec, exec, s[36:37]
	s_lshr_b32 s4, s4, 4
	s_add_i32 s4, s4, 16
	s_ashr_i32 s20, s18, 11
	s_and_b64 s[16:17], s[22:23], exec
	s_cselect_b32 s4, s20, s4
	v_mad_i64_i32 v[38:39], s[16:17], s4, v29, v[18:19]
	s_waitcnt lgkmcnt(0)
	global_load_dwordx4 v[42:45], v[16:17], off
	global_load_dwordx4 v[76:79], v[38:39], off
	global_load_dwordx4 v[46:49], v[16:17], off offset:1024
	global_load_dwordx4 v[82:85], v[38:39], off offset:1024
	global_load_dwordx4 v[64:67], v[16:17], off offset:2048
	global_load_dwordx4 v[86:89], v[38:39], off offset:2048
	global_load_dwordx4 v[72:75], v[16:17], off offset:3072
	global_load_dwordx4 v[90:93], v[38:39], off offset:3072
	s_lshl_b64 s[16:17], s[34:35], 11
	v_lshl_add_u64 v[40:41], v[20:21], 0, s[16:17]
	s_add_u32 s18, s18, s24
	s_addc_u32 s19, s19, s25
	s_add_u32 s10, s10, s12
	s_addc_u32 s11, s11, s13
	s_cmp_gt_i32 s18, 0x807f
	s_waitcnt vmcnt(6)
	v_pk_mul_f32 v[14:15], v[44:45], v[14:15]
	v_pk_mul_f32 v[12:13], v[42:43], v[12:13]
	v_pk_add_f32 v[78:79], v[78:79], 1.0 op_sel_hi:[1,0]
	v_pk_add_f32 v[76:77], v[76:77], 1.0 op_sel_hi:[1,0]
	s_nop 0
	v_pk_mul_f32 v[14:15], v[78:79], v[14:15]
	v_pk_mul_f32 v[12:13], v[76:77], v[12:13]
	s_nop 0
	v_cvt_pk_bf16_f32 v12, v12, v13
	v_cvt_pk_bf16_f32 v13, v14, v15
	global_store_dwordx2 v[40:41], v[12:13], off
	s_waitcnt vmcnt(5)
	v_pk_mul_f32 v[10:11], v[48:49], v[10:11]
	v_pk_mul_f32 v[8:9], v[46:47], v[8:9]
	v_pk_add_f32 v[84:85], v[84:85], 1.0 op_sel_hi:[1,0]
	v_pk_add_f32 v[82:83], v[82:83], 1.0 op_sel_hi:[1,0]
	s_nop 0
	v_pk_mul_f32 v[10:11], v[84:85], v[10:11]
	v_pk_mul_f32 v[8:9], v[82:83], v[8:9]
	s_nop 0
	v_cvt_pk_bf16_f32 v8, v8, v9
	v_cvt_pk_bf16_f32 v9, v10, v11
	global_store_dwordx2 v[40:41], v[8:9], off offset:512
	s_waitcnt vmcnt(4)
	v_pk_mul_f32 v[6:7], v[66:67], v[6:7]
	v_pk_mul_f32 v[4:5], v[64:65], v[4:5]
	v_pk_add_f32 v[88:89], v[88:89], 1.0 op_sel_hi:[1,0]
	v_pk_add_f32 v[86:87], v[86:87], 1.0 op_sel_hi:[1,0]
	s_nop 0
	v_pk_mul_f32 v[6:7], v[88:89], v[6:7]
	v_pk_mul_f32 v[4:5], v[86:87], v[4:5]
	s_nop 0
	v_cvt_pk_bf16_f32 v4, v4, v5
	v_cvt_pk_bf16_f32 v5, v6, v7
	global_store_dwordx2 v[40:41], v[4:5], off offset:1024
	s_waitcnt vmcnt(3)
	v_pk_mul_f32 v[2:3], v[74:75], v[2:3]
	v_pk_mul_f32 v[0:1], v[72:73], v[0:1]
	v_pk_add_f32 v[92:93], v[92:93], 1.0 op_sel_hi:[1,0]
	v_pk_add_f32 v[90:91], v[90:91], 1.0 op_sel_hi:[1,0]
	s_nop 0
	v_pk_mul_f32 v[2:3], v[92:93], v[2:3]
	v_pk_mul_f32 v[0:1], v[90:91], v[0:1]
	s_nop 0
	v_cvt_pk_bf16_f32 v0, v0, v1
	v_cvt_pk_bf16_f32 v1, v2, v3
	global_store_dwordx2 v[40:41], v[0:1], off offset:1536
	s_cbranch_scc1 .LBB0_178
